# decode waves beside a running recurrence stop taking tickets when fewer than 3072 tasks remain (they hold the ticket until the recurrence is done)
# baseline (speedup 1.0000x reference)
; __device__ __forceinline__ void sb_decode_wave_loop(const Params& P, float* lds) {
;     ...
;     for (;;) {
;         const int t = __builtin_amdgcn_readfirstlane((int)nxt);
;         if (t >= DEC_NTASK) break;
;         if (lane == 0) nxt = atomicAdd(qd, 2u);
;         bool thin = false;
;         bool scan_running = false;
;         if (SC_THIN && blockIdx.x < 96) { constexpr unsigned NCHU = SEQ / 16; scan_running = scw[1] < NCHU || scw[2] < NCHU || scw[3] < NCHU || scw[4] < NCHU; thin = scan_running; }
;         thin = true;
;         if (blockIdx.x < 96 && scan_running) { sb_decode_task<4>(P, lds, t); sb_decode_task<4>(P, lds, t + 1); }
;         else if (thin) { sb_decode_task<8>(P, lds, t); sb_decode_task<8>(P, lds, t + 1); }
;         else { sb_decode_task<16>(P, lds, t); sb_decode_task<16>(P, lds, t + 1); }
;     }
.LBB0_1274:
	s_or_b64 exec, exec, s[0:1]
	s_and_b64 vcc, exec, s[22:23]
	s_cbranch_vccnz .LBB0_1279
	s_cmpk_lt_i32 s34, 0x5400
	s_cbranch_scc1 .LBB0_1279
.Ldec_hold:
	v_mov_b32_e32 v2, 0x23004
	ds_read2_b32 v[2:3], v2 offset1:1
	s_waitcnt lgkmcnt(0)
	v_min_u32_e32 v2, v2, v3
	v_mov_b32_e32 v3, 0x2300c
	ds_read_b32 v3, v3
	s_waitcnt lgkmcnt(0)
	v_min_u32_e32 v2, v2, v3
	v_mov_b32_e32 v3, 0x23010
	ds_read_b32 v3, v3
	s_waitcnt lgkmcnt(0)
	v_min_u32_e32 v2, v2, v3
	v_cmp_gt_u32_e32 vcc, 0x100, v2
	s_cbranch_vccz .LBB0_1279
	s_sleep 32
	s_branch .Ldec_hold
	v_mov_b32_e32 v2, s42
	ds_read_b32 v2, v2
	s_movk_i32 s3, 0xff
	s_movk_i32 s2, 0x100
	s_waitcnt lgkmcnt(0)
	v_cmp_lt_u32_e32 vcc, s3, v2
	v_cmp_gt_u32_e64 s[0:1], s2, v2
	s_cbranch_vccz .LBB0_1280
	v_readlane_b32 s0, v252, 60
	s_nop 1
	v_mov_b32_e32 v2, s0
	ds_read_b32 v2, v2
	s_waitcnt lgkmcnt(0)
	v_cmp_lt_u32_e32 vcc, s3, v2
	v_cmp_gt_u32_e64 s[0:1], s2, v2
	s_cbranch_vccz .LBB0_1280
	v_readlane_b32 s0, v252, 58
	s_nop 1
	v_mov_b32_e32 v2, s0
	ds_read_b32 v2, v2
	s_waitcnt lgkmcnt(0)
	v_cmp_lt_u32_e32 vcc, s3, v2
	v_cmp_gt_u32_e64 s[0:1], s2, v2
	s_cbranch_vccz .LBB0_1280
	v_mov_b32_e32 v2, s94
	ds_read_b32 v2, v2
	s_mov_b64 s[0:1], -1
	s_waitcnt lgkmcnt(0)
	v_cmp_lt_u32_e64 s[2:3], s3, v2
	s_and_b64 vcc, exec, s[2:3]
	s_mul_hi_i32 s2, s34, 0x2aaaaaab
	s_cbranch_vccnz .LBB0_1281
	s_branch .LBB0_1418
